# barrier: leader no longer issues the per-XCC release atomic (nobody reads it since non-leaders spin on the cross-XCD word); on top of v138
# baseline (speedup 1.0000x reference)
.LBB0_1531:
	s_or_b64 exec, exec, s[2:3]
	s_mov_b64 s[2:3], exec
	v_mbcnt_lo_u32_b32 v1, s2, 0
	v_mbcnt_hi_u32_b32 v1, s3, v1
	v_cmp_eq_u32_e32 vcc, 0, v1
	s_waitcnt vmcnt(0)
	buffer_inv sc1
	s_and_saveexec_b64 s[4:5], vcc
	s_cbranch_execz .LBB0_158
	s_bcnt1_i32_b64 s2, s[2:3]
	v_mov_b32_e32 v1, s2
	v_readlane_b32 s2, v244, 62
	v_readlane_b32 s3, v244, 63
	s_nop 4
	s_branch .LBB0_158
